# baseline (speedup 1.0000x reference)
; __global__ void __launch_bounds__(256, 2) trunk_fwd(Params p) {
;     ...
;   if (phi > 1000) cg::this_grid().sync();
.LBB0_14:
	s_sleep 0
	global_load_dword v2, v0, s[2:3] offset:32 sc1
	s_waitcnt vmcnt(0)
	v_and_b32_e32 v2, 0xffff0000, v2
	v_cmp_ne_u32_e32 vcc, v2, v1
	s_or_b64 s[4:5], vcc, s[4:5]
	s_andn2_b64 exec, exec, s[4:5]
	s_cbranch_execnz .LBB0_14

; DI unsigned xb_ld(unsigned* p) { return __hip_atomic_load(p, __ATOMIC_RELAXED, __HIP_MEMORY_SCOPE_AGENT); }
; DI void xcd_barrier_complete(unsigned* bar, unsigned x, unsigned& nloc, unsigned& nx) {
;     ...
;   for (;;) {
;     sum = 0u; cnt = 0u; mine = 0u;
; #pragma unroll
;     for (unsigned j = 0; j < 16; ++j) { const unsigned c = xb_ld(&bar[XB_XCNT(j)]); sum += c; cnt += (c > 0u) ? 1u : 0u; mine = (j == x) ? c : mine; }
;     if (sum == G) break;
;     __builtin_amdgcn_s_sleep(1);
;     if ((++sp & 255u) == 0u) { if (xb_ld(&bar[XB_TMO])) break; if (sp > XB_SPIN_CAP) { atomicAdd(&bar[XB_TMO], 1u); break; } }
;   }
.LBB0_23:
	global_load_dword v15, v16, s[44:45] offset:1024 sc1
	global_load_dword v0, v16, s[44:45] offset:1280 sc1
	global_load_dword v1, v16, s[44:45] offset:1536 sc1
	global_load_dword v2, v16, s[44:45] offset:1792 sc1
	global_load_dword v3, v16, s[44:45] offset:2048 sc1
	global_load_dword v4, v16, s[44:45] offset:2304 sc1
	global_load_dword v5, v16, s[44:45] offset:2560 sc1
	global_load_dword v6, v16, s[44:45] offset:2816 sc1
	global_load_dword v7, v16, s[44:45] offset:3072 sc1
	global_load_dword v8, v16, s[44:45] offset:3328 sc1
	global_load_dword v9, v16, s[44:45] offset:3584 sc1
	global_load_dword v10, v16, s[44:45] offset:3840 sc1
	global_load_dword v11, v16, s[0:1] sc1
	global_load_dword v12, v16, s[6:7] sc1
	global_load_dword v13, v16, s[8:9] sc1
	global_load_dword v14, v16, s[10:11] sc1
	s_mov_b64 s[12:13], -1
	s_mov_b64 s[14:15], -1
	s_waitcnt vmcnt(14)
	v_add_u32_e32 v17, v0, v15
	s_waitcnt vmcnt(13)
	v_add_u32_e32 v17, v17, v1
	s_waitcnt vmcnt(12)
	v_add_u32_e32 v17, v17, v2
	s_waitcnt vmcnt(11)
	v_add_u32_e32 v17, v17, v3
	s_waitcnt vmcnt(10)
	v_add_u32_e32 v17, v17, v4
	s_waitcnt vmcnt(9)
	v_add_u32_e32 v17, v17, v5
	s_waitcnt vmcnt(8)
	v_add_u32_e32 v17, v17, v6
	s_waitcnt vmcnt(7)
	v_add_u32_e32 v17, v17, v7
	s_waitcnt vmcnt(6)
	v_add_u32_e32 v17, v17, v8
	s_waitcnt vmcnt(5)
	v_add_u32_e32 v17, v17, v9
	s_waitcnt vmcnt(4)
	v_add_u32_e32 v17, v17, v10
	s_waitcnt vmcnt(3)
	v_add_u32_e32 v17, v17, v11
	s_waitcnt vmcnt(2)
	v_add_u32_e32 v17, v17, v12
	s_waitcnt vmcnt(1)
	v_add_u32_e32 v17, v17, v13
	s_waitcnt vmcnt(0)
	v_add_u32_e32 v17, v17, v14
	v_cmp_eq_u32_e32 vcc, s18, v17
	s_cbranch_vccnz .LBB0_22
	s_and_b32 s12, s19, 0xff
	s_cmp_eq_u32 s12, 0
	s_mov_b64 s[12:13], -1
	s_mov_b64 s[16:17], -1
	s_sleep 0
	s_cbranch_scc0 .LBB0_27
	global_load_dword v17, v16, s[44:45] offset:512 sc1
	s_waitcnt vmcnt(0)
	v_cmp_eq_u32_e32 vcc, 0, v17
	s_cbranch_vccnz .LBB0_29
	s_mov_b64 s[16:17], 0

; DI unsigned xb_ld(unsigned* p) { return __hip_atomic_load(p, __ATOMIC_RELAXED, __HIP_MEMORY_SCOPE_AGENT); }
; DI unsigned xb_add(unsigned* p, unsigned v) { return __hip_atomic_fetch_add(p, v, __ATOMIC_RELAXED, __HIP_MEMORY_SCOPE_AGENT); }
; #define XB_SPIN(cond, bar) do { unsigned _sp = 0; while (cond) { __builtin_amdgcn_s_sleep(1); \
;     if ((++_sp & 255u) == 0u) { if (xb_ld(&(bar)[XB_TMO])) break; if (_sp > XB_SPIN_CAP) { atomicAdd(&(bar)[XB_TMO], 1u); break; } } } } while (0)
; DI void xcd_barrier(const XcdBarrier& b) {
;     ...
;       else XB_SPIN(xb_ld(&bar[XB_TOPGEN]) == tg, bar);
;       __builtin_amdgcn_fence(__ATOMIC_ACQUIRE, "agent");
;       xb_add(&bar[XB_XGEN(b.x)], 1u);
;       asm volatile("s_waitcnt vmcnt(0)" ::: "memory");
;     } else {
;       XB_SPIN(xb_ld(&bar[XB_XGEN(b.x)]) == gen, bar);
.LBB0_41:
	s_and_b32 s18, s22, 0xff
	s_mov_b64 s[16:17], -1
	s_cmp_lg_u32 s18, 0
	s_mov_b64 s[20:21], -1
	s_sleep 0
	s_cbranch_scc1 .LBB0_44
	global_load_dword v2, v0, s[44:45] offset:512 sc1
	s_waitcnt vmcnt(0)
	v_cmp_eq_u32_e32 vcc, 0, v2
	s_cbranch_vccnz .LBB0_46
	s_mov_b64 s[20:21], 0
	s_mov_b64 s[18:19], -1

; DI unsigned xb_ld(unsigned* p) { return __hip_atomic_load(p, __ATOMIC_RELAXED, __HIP_MEMORY_SCOPE_AGENT); }
; DI unsigned xb_add(unsigned* p, unsigned v) { return __hip_atomic_fetch_add(p, v, __ATOMIC_RELAXED, __HIP_MEMORY_SCOPE_AGENT); }
; #define XB_SPIN(cond, bar) do { unsigned _sp = 0; while (cond) { __builtin_amdgcn_s_sleep(1); \
;     if ((++_sp & 255u) == 0u) { if (xb_ld(&(bar)[XB_TMO])) break; if (_sp > XB_SPIN_CAP) { atomicAdd(&(bar)[XB_TMO], 1u); break; } } } } while (0)
; DI void xcd_barrier(const XcdBarrier& b) {
;     ...
;       else XB_SPIN(xb_ld(&bar[XB_TOPGEN]) == tg, bar);
;       __builtin_amdgcn_fence(__ATOMIC_ACQUIRE, "agent");
;       xb_add(&bar[XB_XGEN(b.x)], 1u);
;       asm volatile("s_waitcnt vmcnt(0)" ::: "memory");
;     } else {
;       XB_SPIN(xb_ld(&bar[XB_XGEN(b.x)]) == gen, bar);
.LBB0_58:
	s_and_b32 s18, s24, 0xff
	s_cmp_lg_u32 s18, 0
	s_mov_b64 s[20:21], -1
	s_sleep 0
	s_cbranch_scc1 .LBB0_61
	global_load_dword v1, v0, s[10:11] sc1
	s_waitcnt vmcnt(0)
	v_cmp_eq_u32_e32 vcc, 0, v1
	s_cbranch_vccnz .LBB0_63
	s_mov_b64 s[20:21], 0
	s_mov_b64 s[18:19], -1

; DI unsigned xb_ld(unsigned* p) { return __hip_atomic_load(p, __ATOMIC_RELAXED, __HIP_MEMORY_SCOPE_AGENT); }
; DI void xcd_barrier_complete(unsigned* bar, unsigned x, unsigned& nloc, unsigned& nx) {
;     ...
;   for (;;) {
;     sum = 0u; cnt = 0u; mine = 0u;
; #pragma unroll
;     for (unsigned j = 0; j < 16; ++j) { const unsigned c = xb_ld(&bar[XB_XCNT(j)]); sum += c; cnt += (c > 0u) ? 1u : 0u; mine = (j == x) ? c : mine; }
;     if (sum == G) break;
;     __builtin_amdgcn_s_sleep(1);
;     if ((++sp & 255u) == 0u) { if (xb_ld(&bar[XB_TMO])) break; if (sp > XB_SPIN_CAP) { atomicAdd(&bar[XB_TMO], 1u); break; } }
;   }
.LBB0_162:
	global_load_dword v15, v16, s[44:45] offset:1024 sc1
	global_load_dword v0, v16, s[44:45] offset:1280 sc1
	global_load_dword v1, v16, s[44:45] offset:1536 sc1
	global_load_dword v2, v16, s[44:45] offset:1792 sc1
	global_load_dword v3, v16, s[44:45] offset:2048 sc1
	global_load_dword v4, v16, s[44:45] offset:2304 sc1
	global_load_dword v5, v16, s[44:45] offset:2560 sc1
	global_load_dword v6, v16, s[44:45] offset:2816 sc1
	global_load_dword v7, v16, s[44:45] offset:3072 sc1
	global_load_dword v8, v16, s[44:45] offset:3328 sc1
	global_load_dword v9, v16, s[44:45] offset:3584 sc1
	global_load_dword v10, v16, s[44:45] offset:3840 sc1
	global_load_dword v11, v16, s[0:1] sc1
	global_load_dword v12, v16, s[4:5] sc1
	global_load_dword v13, v16, s[6:7] sc1
	global_load_dword v14, v16, s[8:9] sc1
	s_mov_b64 s[10:11], -1
	s_mov_b64 s[12:13], -1
	s_waitcnt vmcnt(14)
	v_add_u32_e32 v17, v0, v15
	s_waitcnt vmcnt(13)
	v_add_u32_e32 v17, v17, v1
	s_waitcnt vmcnt(12)
	v_add_u32_e32 v17, v17, v2
	s_waitcnt vmcnt(11)
	v_add_u32_e32 v17, v17, v3
	s_waitcnt vmcnt(10)
	v_add_u32_e32 v17, v17, v4
	s_waitcnt vmcnt(9)
	v_add_u32_e32 v17, v17, v5
	s_waitcnt vmcnt(8)
	v_add_u32_e32 v17, v17, v6
	s_waitcnt vmcnt(7)
	v_add_u32_e32 v17, v17, v7
	s_waitcnt vmcnt(6)
	v_add_u32_e32 v17, v17, v8
	s_waitcnt vmcnt(5)
	v_add_u32_e32 v17, v17, v9
	s_waitcnt vmcnt(4)
	v_add_u32_e32 v17, v17, v10
	s_waitcnt vmcnt(3)
	v_add_u32_e32 v17, v17, v11
	s_waitcnt vmcnt(2)
	v_add_u32_e32 v17, v17, v12
	s_waitcnt vmcnt(1)
	v_add_u32_e32 v17, v17, v13
	s_waitcnt vmcnt(0)
	v_add_u32_e32 v17, v17, v14
	v_cmp_eq_u32_e32 vcc, s18, v17
	s_cbranch_vccnz .LBB0_161
	s_and_b32 s10, s19, 0xff
	s_cmp_eq_u32 s10, 0
	s_mov_b64 s[10:11], -1
	s_mov_b64 s[16:17], -1
	s_sleep 0
	s_cbranch_scc0 .LBB0_166
	global_load_dword v17, v16, s[44:45] offset:512 sc1
	s_waitcnt vmcnt(0)
	v_cmp_eq_u32_e32 vcc, 0, v17
	s_cbranch_vccnz .LBB0_168
	s_mov_b64 s[16:17], 0

; DI unsigned xb_ld(unsigned* p) { return __hip_atomic_load(p, __ATOMIC_RELAXED, __HIP_MEMORY_SCOPE_AGENT); }
; DI unsigned xb_add(unsigned* p, unsigned v) { return __hip_atomic_fetch_add(p, v, __ATOMIC_RELAXED, __HIP_MEMORY_SCOPE_AGENT); }
; #define XB_SPIN(cond, bar) do { unsigned _sp = 0; while (cond) { __builtin_amdgcn_s_sleep(1); \
;     if ((++_sp & 255u) == 0u) { if (xb_ld(&(bar)[XB_TMO])) break; if (_sp > XB_SPIN_CAP) { atomicAdd(&(bar)[XB_TMO], 1u); break; } } } } while (0)
; DI void xcd_barrier(const XcdBarrier& b) {
;     ...
;       else XB_SPIN(xb_ld(&bar[XB_TOPGEN]) == tg, bar);
;       __builtin_amdgcn_fence(__ATOMIC_ACQUIRE, "agent");
;       xb_add(&bar[XB_XGEN(b.x)], 1u);
;       asm volatile("s_waitcnt vmcnt(0)" ::: "memory");
;     } else {
;       XB_SPIN(xb_ld(&bar[XB_XGEN(b.x)]) == gen, bar);
.LBB0_197:
	s_and_b32 s18, s24, 0xff
	s_cmp_lg_u32 s18, 0
	s_mov_b64 s[20:21], -1
	s_sleep 0
	s_cbranch_scc1 .LBB0_200
	global_load_dword v1, v0, s[8:9] sc1
	s_waitcnt vmcnt(0)
	v_cmp_eq_u32_e32 vcc, 0, v1
	s_cbranch_vccnz .LBB0_202
	s_mov_b64 s[20:21], 0
	s_mov_b64 s[18:19], -1

; DI unsigned xb_ld(unsigned* p) { return __hip_atomic_load(p, __ATOMIC_RELAXED, __HIP_MEMORY_SCOPE_AGENT); }
; DI void xcd_barrier_complete(unsigned* bar, unsigned x, unsigned& nloc, unsigned& nx) {
;     ...
;   for (;;) {
;     sum = 0u; cnt = 0u; mine = 0u;
; #pragma unroll
;     for (unsigned j = 0; j < 16; ++j) { const unsigned c = xb_ld(&bar[XB_XCNT(j)]); sum += c; cnt += (c > 0u) ? 1u : 0u; mine = (j == x) ? c : mine; }
;     if (sum == G) break;
;     __builtin_amdgcn_s_sleep(1);
;     if ((++sp & 255u) == 0u) { if (xb_ld(&bar[XB_TMO])) break; if (sp > XB_SPIN_CAP) { atomicAdd(&bar[XB_TMO], 1u); break; } }
;   }
.LBB0_686:
	global_load_dword v15, v16, s[44:45] offset:1024 sc1
	global_load_dword v0, v16, s[44:45] offset:1280 sc1
	global_load_dword v1, v16, s[44:45] offset:1536 sc1
	global_load_dword v2, v16, s[44:45] offset:1792 sc1
	global_load_dword v3, v16, s[44:45] offset:2048 sc1
	global_load_dword v4, v16, s[44:45] offset:2304 sc1
	global_load_dword v5, v16, s[44:45] offset:2560 sc1
	global_load_dword v6, v16, s[44:45] offset:2816 sc1
	global_load_dword v7, v16, s[44:45] offset:3072 sc1
	global_load_dword v8, v16, s[44:45] offset:3328 sc1
	global_load_dword v9, v16, s[44:45] offset:3584 sc1
	global_load_dword v10, v16, s[44:45] offset:3840 sc1
	global_load_dword v11, v16, s[0:1] sc1
	global_load_dword v12, v16, s[4:5] sc1
	global_load_dword v13, v16, s[6:7] sc1
	global_load_dword v14, v16, s[10:11] sc1
	s_mov_b64 s[12:13], -1
	s_mov_b64 s[14:15], -1
	s_waitcnt vmcnt(14)
	v_add_u32_e32 v17, v0, v15
	s_waitcnt vmcnt(13)
	v_add_u32_e32 v17, v17, v1
	s_waitcnt vmcnt(12)
	v_add_u32_e32 v17, v17, v2
	s_waitcnt vmcnt(11)
	v_add_u32_e32 v17, v17, v3
	s_waitcnt vmcnt(10)
	v_add_u32_e32 v17, v17, v4
	s_waitcnt vmcnt(9)
	v_add_u32_e32 v17, v17, v5
	s_waitcnt vmcnt(8)
	v_add_u32_e32 v17, v17, v6
	s_waitcnt vmcnt(7)
	v_add_u32_e32 v17, v17, v7
	s_waitcnt vmcnt(6)
	v_add_u32_e32 v17, v17, v8
	s_waitcnt vmcnt(5)
	v_add_u32_e32 v17, v17, v9
	s_waitcnt vmcnt(4)
	v_add_u32_e32 v17, v17, v10
	s_waitcnt vmcnt(3)
	v_add_u32_e32 v17, v17, v11
	s_waitcnt vmcnt(2)
	v_add_u32_e32 v17, v17, v12
	s_waitcnt vmcnt(1)
	v_add_u32_e32 v17, v17, v13
	s_waitcnt vmcnt(0)
	v_add_u32_e32 v17, v17, v14
	v_cmp_eq_u32_e32 vcc, s18, v17
	s_cbranch_vccnz .LBB0_685
	s_and_b32 s12, s19, 0xff
	s_cmp_eq_u32 s12, 0
	s_mov_b64 s[12:13], -1
	s_mov_b64 s[16:17], -1
	s_sleep 0
	s_cbranch_scc0 .LBB0_690
	global_load_dword v17, v16, s[44:45] offset:512 sc1
	s_waitcnt vmcnt(0)
	v_cmp_eq_u32_e32 vcc, 0, v17
	s_cbranch_vccnz .LBB0_692
	s_mov_b64 s[16:17], 0

; DI unsigned xb_ld(unsigned* p) { return __hip_atomic_load(p, __ATOMIC_RELAXED, __HIP_MEMORY_SCOPE_AGENT); }
; DI void xcd_barrier_complete(unsigned* bar, unsigned x, unsigned& nloc, unsigned& nx) {
;     ...
;   for (;;) {
;     sum = 0u; cnt = 0u; mine = 0u;
; #pragma unroll
;     for (unsigned j = 0; j < 16; ++j) { const unsigned c = xb_ld(&bar[XB_XCNT(j)]); sum += c; cnt += (c > 0u) ? 1u : 0u; mine = (j == x) ? c : mine; }
;     if (sum == G) break;
;     __builtin_amdgcn_s_sleep(1);
;     if ((++sp & 255u) == 0u) { if (xb_ld(&bar[XB_TMO])) break; if (sp > XB_SPIN_CAP) { atomicAdd(&bar[XB_TMO], 1u); break; } }
;   }
.LBB0_750:
	global_load_dword v15, v16, s[44:45] offset:1024 sc1
	global_load_dword v0, v16, s[44:45] offset:1280 sc1
	global_load_dword v1, v16, s[44:45] offset:1536 sc1
	global_load_dword v2, v16, s[44:45] offset:1792 sc1
	global_load_dword v3, v16, s[44:45] offset:2048 sc1
	global_load_dword v4, v16, s[44:45] offset:2304 sc1
	global_load_dword v5, v16, s[44:45] offset:2560 sc1
	global_load_dword v6, v16, s[44:45] offset:2816 sc1
	global_load_dword v7, v16, s[44:45] offset:3072 sc1
	global_load_dword v8, v16, s[44:45] offset:3328 sc1
	global_load_dword v9, v16, s[44:45] offset:3584 sc1
	global_load_dword v10, v16, s[44:45] offset:3840 sc1
	global_load_dword v11, v16, s[0:1] sc1
	global_load_dword v12, v16, s[4:5] sc1
	global_load_dword v13, v16, s[6:7] sc1
	global_load_dword v14, v16, s[8:9] sc1
	s_mov_b64 s[10:11], -1
	s_mov_b64 s[12:13], -1
	s_waitcnt vmcnt(14)
	v_add_u32_e32 v17, v0, v15
	s_waitcnt vmcnt(13)
	v_add_u32_e32 v17, v17, v1
	s_waitcnt vmcnt(12)
	v_add_u32_e32 v17, v17, v2
	s_waitcnt vmcnt(11)
	v_add_u32_e32 v17, v17, v3
	s_waitcnt vmcnt(10)
	v_add_u32_e32 v17, v17, v4
	s_waitcnt vmcnt(9)
	v_add_u32_e32 v17, v17, v5
	s_waitcnt vmcnt(8)
	v_add_u32_e32 v17, v17, v6
	s_waitcnt vmcnt(7)
	v_add_u32_e32 v17, v17, v7
	s_waitcnt vmcnt(6)
	v_add_u32_e32 v17, v17, v8
	s_waitcnt vmcnt(5)
	v_add_u32_e32 v17, v17, v9
	s_waitcnt vmcnt(4)
	v_add_u32_e32 v17, v17, v10
	s_waitcnt vmcnt(3)
	v_add_u32_e32 v17, v17, v11
	s_waitcnt vmcnt(2)
	v_add_u32_e32 v17, v17, v12
	s_waitcnt vmcnt(1)
	v_add_u32_e32 v17, v17, v13
	s_waitcnt vmcnt(0)
	v_add_u32_e32 v17, v17, v14
	v_cmp_eq_u32_e32 vcc, s16, v17
	s_cbranch_vccnz .LBB0_749
	s_and_b32 s10, s17, 0xff
	s_cmp_eq_u32 s10, 0
	s_mov_b64 s[10:11], -1
	s_mov_b64 s[14:15], -1
	s_sleep 0
	s_cbranch_scc0 .LBB0_754
	global_load_dword v17, v16, s[44:45] offset:512 sc1
	s_waitcnt vmcnt(0)
	v_cmp_eq_u32_e32 vcc, 0, v17
	s_cbranch_vccnz .LBB0_756
	s_mov_b64 s[14:15], 0

; DI unsigned xb_ld(unsigned* p) { return __hip_atomic_load(p, __ATOMIC_RELAXED, __HIP_MEMORY_SCOPE_AGENT); }
; DI unsigned xb_add(unsigned* p, unsigned v) { return __hip_atomic_fetch_add(p, v, __ATOMIC_RELAXED, __HIP_MEMORY_SCOPE_AGENT); }
; #define XB_SPIN(cond, bar) do { unsigned _sp = 0; while (cond) { __builtin_amdgcn_s_sleep(1); \
;     if ((++_sp & 255u) == 0u) { if (xb_ld(&(bar)[XB_TMO])) break; if (_sp > XB_SPIN_CAP) { atomicAdd(&(bar)[XB_TMO], 1u); break; } } } } while (0)
; DI void xcd_barrier(const XcdBarrier& b) {
;     ...
;       else XB_SPIN(xb_ld(&bar[XB_TOPGEN]) == tg, bar);
;       __builtin_amdgcn_fence(__ATOMIC_ACQUIRE, "agent");
;       xb_add(&bar[XB_XGEN(b.x)], 1u);
;       asm volatile("s_waitcnt vmcnt(0)" ::: "memory");
;     } else {
;       XB_SPIN(xb_ld(&bar[XB_XGEN(b.x)]) == gen, bar);
.LBB0_768:
	s_and_b32 s16, s20, 0xff
	s_mov_b64 s[14:15], -1
	s_cmp_lg_u32 s16, 0
	s_mov_b64 s[18:19], -1
	s_sleep 0
	s_cbranch_scc1 .LBB0_771
	global_load_dword v2, v0, s[44:45] offset:512 sc1
	s_waitcnt vmcnt(0)
	v_cmp_eq_u32_e32 vcc, 0, v2
	s_cbranch_vccnz .LBB0_773
	s_mov_b64 s[18:19], 0
	s_mov_b64 s[16:17], -1

; DI unsigned xb_ld(unsigned* p) { return __hip_atomic_load(p, __ATOMIC_RELAXED, __HIP_MEMORY_SCOPE_AGENT); }
; DI unsigned xb_add(unsigned* p, unsigned v) { return __hip_atomic_fetch_add(p, v, __ATOMIC_RELAXED, __HIP_MEMORY_SCOPE_AGENT); }
; #define XB_SPIN(cond, bar) do { unsigned _sp = 0; while (cond) { __builtin_amdgcn_s_sleep(1); \
;     if ((++_sp & 255u) == 0u) { if (xb_ld(&(bar)[XB_TMO])) break; if (_sp > XB_SPIN_CAP) { atomicAdd(&(bar)[XB_TMO], 1u); break; } } } } while (0)
; DI void xcd_barrier(const XcdBarrier& b) {
;     ...
;       else XB_SPIN(xb_ld(&bar[XB_TOPGEN]) == tg, bar);
;       __builtin_amdgcn_fence(__ATOMIC_ACQUIRE, "agent");
;       xb_add(&bar[XB_XGEN(b.x)], 1u);
;       asm volatile("s_waitcnt vmcnt(0)" ::: "memory");
;     } else {
;       XB_SPIN(xb_ld(&bar[XB_XGEN(b.x)]) == gen, bar);
.LBB0_785:
	s_and_b32 s16, s22, 0xff
	s_cmp_lg_u32 s16, 0
	s_mov_b64 s[18:19], -1
	s_sleep 0
	s_cbranch_scc1 .LBB0_788
	global_load_dword v1, v0, s[8:9] sc1
	s_waitcnt vmcnt(0)
	v_cmp_eq_u32_e32 vcc, 0, v1
	s_cbranch_vccnz .LBB0_790
	s_mov_b64 s[18:19], 0
	s_mov_b64 s[16:17], -1

; DI unsigned xb_ld(unsigned* p) { return __hip_atomic_load(p, __ATOMIC_RELAXED, __HIP_MEMORY_SCOPE_AGENT); }
; DI unsigned xb_add(unsigned* p, unsigned v) { return __hip_atomic_fetch_add(p, v, __ATOMIC_RELAXED, __HIP_MEMORY_SCOPE_AGENT); }
; #define XB_SPIN(cond, bar) do { unsigned _sp = 0; while (cond) { __builtin_amdgcn_s_sleep(1); \
;     if ((++_sp & 255u) == 0u) { if (xb_ld(&(bar)[XB_TMO])) break; if (_sp > XB_SPIN_CAP) { atomicAdd(&(bar)[XB_TMO], 1u); break; } } } } while (0)
; DI void xcd_barrier(const XcdBarrier& b) {
;     ...
;       else XB_SPIN(xb_ld(&bar[XB_TOPGEN]) == tg, bar);
;       __builtin_amdgcn_fence(__ATOMIC_ACQUIRE, "agent");
;       xb_add(&bar[XB_XGEN(b.x)], 1u);
;       asm volatile("s_waitcnt vmcnt(0)" ::: "memory");
;     } else {
;       XB_SPIN(xb_ld(&bar[XB_XGEN(b.x)]) == gen, bar);
.LBB0_1088:
	s_and_b32 s16, s24, 0xff
	s_cmp_lg_u32 s16, 0
	s_mov_b64 s[18:19], -1
	s_sleep 0
	s_cbranch_scc1 .LBB0_1091
	global_load_dword v1, v0, s[8:9] sc1
	s_waitcnt vmcnt(0)
	v_cmp_eq_u32_e32 vcc, 0, v1
	s_cbranch_vccnz .LBB0_1093
	s_mov_b64 s[18:19], 0
	s_mov_b64 s[16:17], -1

; DI void diff_attn_phase(const Params& p, char* smem) {
;     ...
;     if (tid == 0) {
;       unsigned sp = 0;
;       while (__hip_atomic_load(p.pflag + pair, __ATOMIC_RELAXED, __HIP_MEMORY_SCOPE_AGENT) == 0u) { __builtin_amdgcn_s_sleep(2); if (++sp > (1u << 26)) break; }
;       __builtin_amdgcn_fence(__ATOMIC_ACQUIRE, "agent");
;       asm volatile("s_waitcnt vmcnt(0)" ::: "memory");
;     }
.LBB0_1505:
	global_load_dword v0, v1, s[4:5] sc1
	s_mov_b64 s[6:7], -1
	s_waitcnt vmcnt(0)
	v_cmp_ne_u32_e32 vcc, 0, v0
	s_cbranch_vccnz .LBB0_1504
	s_sleep 0
	global_load_dword v0, v1, s[4:5] sc1
	s_waitcnt vmcnt(0)
	v_cmp_eq_u32_e32 vcc, 0, v0
	s_cbranch_vccz .LBB0_1504
	s_sleep 0
	global_load_dword v0, v1, s[4:5] sc1
	s_waitcnt vmcnt(0)
	v_cmp_eq_u32_e32 vcc, 0, v0
	s_cbranch_vccz .LBB0_1504
	s_sleep 0
	global_load_dword v0, v1, s[4:5] sc1
	s_waitcnt vmcnt(0)
	v_cmp_eq_u32_e32 vcc, 0, v0
	s_cbranch_vccz .LBB0_1504
	s_sleep 0
	global_load_dword v0, v1, s[4:5] sc1
	s_waitcnt vmcnt(0)
	v_cmp_eq_u32_e32 vcc, 0, v0
	s_cbranch_vccz .LBB0_1504
	s_add_i32 s8, s8, -5
	s_cmp_eq_u32 s8, 0
	s_cselect_b64 s[6:7], -1, 0
	s_sleep 0
	s_branch .LBB0_1504

; DI unsigned xb_ld(unsigned* p) { return __hip_atomic_load(p, __ATOMIC_RELAXED, __HIP_MEMORY_SCOPE_AGENT); }
; DI void xcd_barrier_complete(unsigned* bar, unsigned x, unsigned& nloc, unsigned& nx) {
;     ...
;   for (;;) {
;     sum = 0u; cnt = 0u; mine = 0u;
; #pragma unroll
;     for (unsigned j = 0; j < 16; ++j) { const unsigned c = xb_ld(&bar[XB_XCNT(j)]); sum += c; cnt += (c > 0u) ? 1u : 0u; mine = (j == x) ? c : mine; }
;     if (sum == G) break;
;     __builtin_amdgcn_s_sleep(1);
;     if ((++sp & 255u) == 0u) { if (xb_ld(&bar[XB_TMO])) break; if (sp > XB_SPIN_CAP) { atomicAdd(&bar[XB_TMO], 1u); break; } }
;   }
.LBB0_1648:
	global_load_dword v15, v16, s[44:45] offset:1024 sc1
	global_load_dword v0, v16, s[44:45] offset:1280 sc1
	global_load_dword v1, v16, s[44:45] offset:1536 sc1
	global_load_dword v2, v16, s[44:45] offset:1792 sc1
	global_load_dword v3, v16, s[44:45] offset:2048 sc1
	global_load_dword v4, v16, s[44:45] offset:2304 sc1
	global_load_dword v5, v16, s[44:45] offset:2560 sc1
	global_load_dword v6, v16, s[44:45] offset:2816 sc1
	global_load_dword v7, v16, s[44:45] offset:3072 sc1
	global_load_dword v8, v16, s[44:45] offset:3328 sc1
	global_load_dword v9, v16, s[44:45] offset:3584 sc1
	global_load_dword v10, v16, s[44:45] offset:3840 sc1
	global_load_dword v11, v16, s[0:1] sc1
	global_load_dword v12, v16, s[4:5] sc1
	global_load_dword v13, v16, s[6:7] sc1
	global_load_dword v14, v16, s[8:9] sc1
	s_mov_b64 s[10:11], -1
	s_mov_b64 s[12:13], -1
	s_waitcnt vmcnt(14)
	v_add_u32_e32 v17, v0, v15
	s_waitcnt vmcnt(13)
	v_add_u32_e32 v17, v17, v1
	s_waitcnt vmcnt(12)
	v_add_u32_e32 v17, v17, v2
	s_waitcnt vmcnt(11)
	v_add_u32_e32 v17, v17, v3
	s_waitcnt vmcnt(10)
	v_add_u32_e32 v17, v17, v4
	s_waitcnt vmcnt(9)
	v_add_u32_e32 v17, v17, v5
	s_waitcnt vmcnt(8)
	v_add_u32_e32 v17, v17, v6
	s_waitcnt vmcnt(7)
	v_add_u32_e32 v17, v17, v7
	s_waitcnt vmcnt(6)
	v_add_u32_e32 v17, v17, v8
	s_waitcnt vmcnt(5)
	v_add_u32_e32 v17, v17, v9
	s_waitcnt vmcnt(4)
	v_add_u32_e32 v17, v17, v10
	s_waitcnt vmcnt(3)
	v_add_u32_e32 v17, v17, v11
	s_waitcnt vmcnt(2)
	v_add_u32_e32 v17, v17, v12
	s_waitcnt vmcnt(1)
	v_add_u32_e32 v17, v17, v13
	s_waitcnt vmcnt(0)
	v_add_u32_e32 v17, v17, v14
	v_cmp_eq_u32_e32 vcc, s18, v17
	s_cbranch_vccnz .LBB0_1647
	s_and_b32 s10, s19, 0xff
	s_cmp_eq_u32 s10, 0
	s_mov_b64 s[10:11], -1
	s_mov_b64 s[14:15], -1
	s_sleep 0
	s_cbranch_scc0 .LBB0_1652
	global_load_dword v17, v16, s[44:45] offset:512 sc1
	s_waitcnt vmcnt(0)
	v_cmp_eq_u32_e32 vcc, 0, v17
	s_cbranch_vccnz .LBB0_1654
	s_mov_b64 s[14:15], 0

; DI unsigned xb_ld(unsigned* p) { return __hip_atomic_load(p, __ATOMIC_RELAXED, __HIP_MEMORY_SCOPE_AGENT); }
; DI unsigned xb_add(unsigned* p, unsigned v) { return __hip_atomic_fetch_add(p, v, __ATOMIC_RELAXED, __HIP_MEMORY_SCOPE_AGENT); }
; #define XB_SPIN(cond, bar) do { unsigned _sp = 0; while (cond) { __builtin_amdgcn_s_sleep(1); \
;     if ((++_sp & 255u) == 0u) { if (xb_ld(&(bar)[XB_TMO])) break; if (_sp > XB_SPIN_CAP) { atomicAdd(&(bar)[XB_TMO], 1u); break; } } } } while (0)
; DI void xcd_barrier(const XcdBarrier& b) {
;     ...
;       else XB_SPIN(xb_ld(&bar[XB_TOPGEN]) == tg, bar);
;       __builtin_amdgcn_fence(__ATOMIC_ACQUIRE, "agent");
;       xb_add(&bar[XB_XGEN(b.x)], 1u);
;       asm volatile("s_waitcnt vmcnt(0)" ::: "memory");
;     } else {
;       XB_SPIN(xb_ld(&bar[XB_XGEN(b.x)]) == gen, bar);
.LBB0_1666:
	s_and_b32 s18, s22, 0xff
	s_mov_b64 s[14:15], -1
	s_cmp_lg_u32 s18, 0
	s_mov_b64 s[20:21], -1
	s_sleep 0
	s_cbranch_scc1 .LBB0_1669
	global_load_dword v2, v0, s[44:45] offset:512 sc1
	s_waitcnt vmcnt(0)
	v_cmp_eq_u32_e32 vcc, 0, v2
	s_cbranch_vccnz .LBB0_1671
	s_mov_b64 s[20:21], 0
	s_mov_b64 s[18:19], -1

; DI unsigned xb_ld(unsigned* p) { return __hip_atomic_load(p, __ATOMIC_RELAXED, __HIP_MEMORY_SCOPE_AGENT); }
; DI void xcd_barrier_complete(unsigned* bar, unsigned x, unsigned& nloc, unsigned& nx) {
;     ...
;   for (;;) {
;     sum = 0u; cnt = 0u; mine = 0u;
; #pragma unroll
;     for (unsigned j = 0; j < 16; ++j) { const unsigned c = xb_ld(&bar[XB_XCNT(j)]); sum += c; cnt += (c > 0u) ? 1u : 0u; mine = (j == x) ? c : mine; }
;     if (sum == G) break;
;     __builtin_amdgcn_s_sleep(1);
;     if ((++sp & 255u) == 0u) { if (xb_ld(&bar[XB_TMO])) break; if (sp > XB_SPIN_CAP) { atomicAdd(&bar[XB_TMO], 1u); break; } }
;   }
.LBB0_2025:
	global_load_dword v15, v16, s[44:45] offset:1024 sc1
	global_load_dword v0, v16, s[44:45] offset:1280 sc1
	global_load_dword v1, v16, s[44:45] offset:1536 sc1
	global_load_dword v2, v16, s[44:45] offset:1792 sc1
	global_load_dword v3, v16, s[44:45] offset:2048 sc1
	global_load_dword v4, v16, s[44:45] offset:2304 sc1
	global_load_dword v5, v16, s[44:45] offset:2560 sc1
	global_load_dword v6, v16, s[44:45] offset:2816 sc1
	global_load_dword v7, v16, s[44:45] offset:3072 sc1
	global_load_dword v8, v16, s[44:45] offset:3328 sc1
	global_load_dword v9, v16, s[44:45] offset:3584 sc1
	global_load_dword v10, v16, s[44:45] offset:3840 sc1
	global_load_dword v11, v16, s[0:1] sc1
	global_load_dword v12, v16, s[6:7] sc1
	global_load_dword v13, v16, s[8:9] sc1
	global_load_dword v14, v16, s[10:11] sc1
	s_mov_b64 s[12:13], -1
	s_mov_b64 s[14:15], -1
	s_waitcnt vmcnt(14)
	v_add_u32_e32 v17, v0, v15
	s_waitcnt vmcnt(13)
	v_add_u32_e32 v17, v17, v1
	s_waitcnt vmcnt(12)
	v_add_u32_e32 v17, v17, v2
	s_waitcnt vmcnt(11)
	v_add_u32_e32 v17, v17, v3
	s_waitcnt vmcnt(10)
	v_add_u32_e32 v17, v17, v4
	s_waitcnt vmcnt(9)
	v_add_u32_e32 v17, v17, v5
	s_waitcnt vmcnt(8)
	v_add_u32_e32 v17, v17, v6
	s_waitcnt vmcnt(7)
	v_add_u32_e32 v17, v17, v7
	s_waitcnt vmcnt(6)
	v_add_u32_e32 v17, v17, v8
	s_waitcnt vmcnt(5)
	v_add_u32_e32 v17, v17, v9
	s_waitcnt vmcnt(4)
	v_add_u32_e32 v17, v17, v10
	s_waitcnt vmcnt(3)
	v_add_u32_e32 v17, v17, v11
	s_waitcnt vmcnt(2)
	v_add_u32_e32 v17, v17, v12
	s_waitcnt vmcnt(1)
	v_add_u32_e32 v17, v17, v13
	s_waitcnt vmcnt(0)
	v_add_u32_e32 v17, v17, v14
	v_cmp_eq_u32_e32 vcc, s2, v17
	s_cbranch_vccnz .LBB0_2024
	s_and_b32 s12, s3, 0xff
	s_cmp_eq_u32 s12, 0
	s_mov_b64 s[12:13], -1
	s_mov_b64 s[16:17], -1
	s_sleep 0
	s_cbranch_scc0 .LBB0_2029
	global_load_dword v17, v16, s[44:45] offset:512 sc1
	s_waitcnt vmcnt(0)
	v_cmp_eq_u32_e32 vcc, 0, v17
	s_cbranch_vccnz .LBB0_2031
	s_mov_b64 s[16:17], 0

; DI unsigned xb_ld(unsigned* p) { return __hip_atomic_load(p, __ATOMIC_RELAXED, __HIP_MEMORY_SCOPE_AGENT); }
; DI unsigned xb_add(unsigned* p, unsigned v) { return __hip_atomic_fetch_add(p, v, __ATOMIC_RELAXED, __HIP_MEMORY_SCOPE_AGENT); }
; #define XB_SPIN(cond, bar) do { unsigned _sp = 0; while (cond) { __builtin_amdgcn_s_sleep(1); \
;     if ((++_sp & 255u) == 0u) { if (xb_ld(&(bar)[XB_TMO])) break; if (_sp > XB_SPIN_CAP) { atomicAdd(&(bar)[XB_TMO], 1u); break; } } } } while (0)
; DI void xcd_barrier(const XcdBarrier& b) {
;     ...
;       else XB_SPIN(xb_ld(&bar[XB_TOPGEN]) == tg, bar);
;       __builtin_amdgcn_fence(__ATOMIC_ACQUIRE, "agent");
;       xb_add(&bar[XB_XGEN(b.x)], 1u);
;       asm volatile("s_waitcnt vmcnt(0)" ::: "memory");
;     } else {
;       XB_SPIN(xb_ld(&bar[XB_XGEN(b.x)]) == gen, bar);
.LBB0_2043:
	s_and_b32 s3, s2, 0xff
	s_mov_b64 s[16:17], -1
	s_cmp_lg_u32 s3, 0
	s_mov_b64 s[20:21], -1
	s_sleep 0
	s_cbranch_scc1 .LBB0_2046
	global_load_dword v2, v0, s[44:45] offset:512 sc1
	s_waitcnt vmcnt(0)
	v_cmp_eq_u32_e32 vcc, 0, v2
	s_cbranch_vccnz .LBB0_2048
	s_mov_b64 s[20:21], 0
	s_mov_b64 s[18:19], -1

; DI unsigned xb_ld(unsigned* p) { return __hip_atomic_load(p, __ATOMIC_RELAXED, __HIP_MEMORY_SCOPE_AGENT); }
; DI unsigned xb_add(unsigned* p, unsigned v) { return __hip_atomic_fetch_add(p, v, __ATOMIC_RELAXED, __HIP_MEMORY_SCOPE_AGENT); }
; #define XB_SPIN(cond, bar) do { unsigned _sp = 0; while (cond) { __builtin_amdgcn_s_sleep(1); \
;     if ((++_sp & 255u) == 0u) { if (xb_ld(&(bar)[XB_TMO])) break; if (_sp > XB_SPIN_CAP) { atomicAdd(&(bar)[XB_TMO], 1u); break; } } } } while (0)
; DI void xcd_barrier(const XcdBarrier& b) {
;     ...
;       else XB_SPIN(xb_ld(&bar[XB_TOPGEN]) == tg, bar);
;       __builtin_amdgcn_fence(__ATOMIC_ACQUIRE, "agent");
;       xb_add(&bar[XB_XGEN(b.x)], 1u);
;       asm volatile("s_waitcnt vmcnt(0)" ::: "memory");
;     } else {
;       XB_SPIN(xb_ld(&bar[XB_XGEN(b.x)]) == gen, bar);
.LBB0_2060:
	s_and_b32 s3, s2, 0xff
	s_cmp_lg_u32 s3, 0
	s_mov_b64 s[20:21], -1
	s_sleep 0
	s_cbranch_scc1 .LBB0_2063
	global_load_dword v1, v0, s[10:11] sc1
	s_waitcnt vmcnt(0)
	v_cmp_eq_u32_e32 vcc, 0, v1
	s_cbranch_vccnz .LBB0_2065
	s_mov_b64 s[20:21], 0
	s_mov_b64 s[18:19], -1
